# attention PV: all four K-step MFMAs of each output accumulator chained back to back
# speedup vs baseline: 1.0038x; 1.0038x over previous
.LBB0_235:
	v_sub_f32_e32 v80, v80, v145
	v_exp_f32_e32 v80, v80
	v_sub_f32_e32 v81, v81, v145
	v_exp_f32_e32 v81, v81
	v_sub_f32_e32 v82, v82, v145
	v_exp_f32_e32 v82, v82
	v_sub_f32_e32 v83, v83, v145
	v_exp_f32_e32 v83, v83
	v_sub_f32_e32 v84, v84, v145
	v_add_f32_e32 v188, 0, v80
	v_exp_f32_e32 v84, v84
	v_sub_f32_e32 v85, v85, v145
	v_add_f32_e32 v188, v81, v188
	v_exp_f32_e32 v85, v85
	v_sub_f32_e32 v86, v86, v145
	v_add_f32_e32 v188, v82, v188
	v_exp_f32_e32 v86, v86
	v_sub_f32_e32 v87, v87, v145
	v_add_f32_e32 v188, v83, v188
	v_exp_f32_e32 v87, v87
	v_sub_f32_e32 v88, v88, v145
	v_add_f32_e32 v188, v84, v188
	v_exp_f32_e32 v88, v88
	v_sub_f32_e32 v89, v89, v145
	v_add_f32_e32 v188, v85, v188
	v_exp_f32_e32 v89, v89
	v_sub_f32_e32 v90, v90, v145
	v_add_f32_e32 v188, v86, v188
	v_exp_f32_e32 v90, v90
	v_sub_f32_e32 v91, v91, v145
	v_add_f32_e32 v188, v87, v188
	v_exp_f32_e32 v91, v91
	v_sub_f32_e32 v92, v92, v145
	v_add_f32_e32 v188, v88, v188
	v_exp_f32_e32 v92, v92
	v_sub_f32_e32 v93, v93, v145
	v_add_f32_e32 v188, v89, v188
	v_exp_f32_e32 v93, v93
	v_sub_f32_e32 v94, v94, v145
	v_add_f32_e32 v188, v90, v188
	v_exp_f32_e32 v94, v94
	v_sub_f32_e32 v95, v95, v145
	v_add_f32_e32 v188, v91, v188
	v_exp_f32_e32 v95, v95
	v_sub_f32_e32 v64, v64, v145
	v_add_f32_e32 v188, v92, v188
	v_exp_f32_e32 v189, v64
	v_sub_f32_e32 v64, v65, v145
	v_add_f32_e32 v188, v93, v188
	v_exp_f32_e32 v190, v64
	v_sub_f32_e32 v64, v66, v145
	v_add_f32_e32 v188, v94, v188
	v_exp_f32_e32 v191, v64
	v_sub_f32_e32 v64, v67, v145
	v_add_f32_e32 v188, v95, v188
	v_exp_f32_e32 v192, v64
	v_sub_f32_e32 v65, v68, v145
	v_add_f32_e32 v64, v189, v188
	v_exp_f32_e32 v188, v65
	v_sub_f32_e32 v65, v69, v145
	v_add_f32_e32 v64, v190, v64
	v_exp_f32_e32 v193, v65
	v_sub_f32_e32 v65, v70, v145
	v_add_f32_e32 v64, v191, v64
	v_exp_f32_e32 v194, v65
	v_sub_f32_e32 v65, v71, v145
	v_add_f32_e32 v64, v192, v64
	v_exp_f32_e32 v195, v65
	v_sub_f32_e32 v65, v72, v145
	v_add_f32_e32 v64, v188, v64
	v_exp_f32_e32 v196, v65
	v_sub_f32_e32 v65, v73, v145
	v_add_f32_e32 v64, v193, v64
	v_exp_f32_e32 v197, v65
	v_sub_f32_e32 v65, v74, v145
	v_add_f32_e32 v64, v194, v64
	v_exp_f32_e32 v198, v65
	v_sub_f32_e32 v65, v75, v145
	v_add_f32_e32 v64, v195, v64
	v_exp_f32_e32 v199, v65
	v_sub_f32_e32 v65, v76, v145
	v_add_f32_e32 v64, v196, v64
	v_exp_f32_e32 v200, v65
	v_sub_f32_e32 v65, v77, v145
	v_add_f32_e32 v64, v197, v64
	v_exp_f32_e32 v201, v65
	v_sub_f32_e32 v65, v78, v145
	v_add_f32_e32 v64, v198, v64
	v_exp_f32_e32 v202, v65
	v_sub_f32_e32 v65, v79, v145
	v_add_f32_e32 v64, v199, v64
	v_exp_f32_e32 v79, v65
	v_add_f32_e32 v64, v200, v64
	v_add_f32_e32 v64, v201, v64
	v_subrev_u32_e32 v151, s26, v176
	v_subrev_u32_e32 v187, s26, v174
	v_add_f32_e32 v64, v202, v64
	v_add_u32_e32 v204, s54, v181
	v_add_f32_e32 v212, v79, v64
	v_cvt_pk_bf16_f32 v64, v80, v81
	v_cvt_pk_bf16_f32 v65, v82, v83
	v_cvt_pk_bf16_f32 v66, v84, v85
	v_cvt_pk_bf16_f32 v67, v86, v87
	v_cvt_pk_bf16_f32 v68, v88, v89
	v_cvt_pk_bf16_f32 v69, v90, v91
	v_cvt_pk_bf16_f32 v70, v92, v93
	v_add_u32_e32 v92, v204, v187
	v_add_u32_e32 v151, v204, v151
	v_cvt_pk_bf16_f32 v71, v94, v95
	v_cvt_pk_bf16_f32 v72, v189, v190
	v_cvt_pk_bf16_f32 v73, v191, v192
	v_cvt_pk_bf16_f32 v74, v188, v193
	v_cvt_pk_bf16_f32 v75, v194, v195
	v_cvt_pk_bf16_f32 v76, v196, v197
	v_cvt_pk_bf16_f32 v77, v198, v199
	v_cvt_pk_bf16_f32 v78, v200, v201
	v_cvt_pk_bf16_f32 v79, v202, v79
	ds_read_b128 v[80:83], v92 offset:16384
	ds_read_b128 v[84:87], v92 offset:20480
	ds_read_b128 v[88:91], v92 offset:24576
	ds_read_b128 v[92:95], v92 offset:28672
	ds_read_b128 v[188:191], v151 offset:16384
	ds_read_b128 v[192:195], v151 offset:20480
	ds_read_b128 v[196:199], v151 offset:24576
	ds_read_b128 v[200:203], v151 offset:28672
	v_subrev_u32_e32 v147, s26, v180
	v_subrev_u32_e32 v149, s26, v178
	v_add_u32_e32 v149, v204, v149
	v_add_u32_e32 v147, v204, v147
	ds_read_b128 v[208:211], v149 offset:16384
	ds_read_b128 v[214:217], v149 offset:20480
	ds_read_b128 v[230:233], v149 offset:24576
	ds_read_b128 v[234:237], v149 offset:28672
	ds_read_b128 v[238:241], v147 offset:16384
	ds_read_b128 v[242:245], v147 offset:20480
	ds_read_b128 v[246:249], v147 offset:24576
	ds_read_b128 v[204:207], v147 offset:28672
	s_setprio 1
	s_waitcnt lgkmcnt(0)
	v_mfma_f32_32x32x16_bf16 v[48:63], v[80:83], v[64:67], v[48:63]
	v_add_f32_e32 v143, v143, v212
	v_mfma_f32_32x32x16_bf16 v[48:63], v[188:191], v[68:71], v[48:63]
	v_mfma_f32_32x32x16_bf16 v[48:63], v[208:211], v[72:75], v[48:63]
	v_mfma_f32_32x32x16_bf16 v[48:63], v[238:241], v[76:79], v[48:63]
	v_mfma_f32_32x32x16_bf16 v[32:47], v[84:87], v[64:67], v[32:47]
	v_mfma_f32_32x32x16_bf16 v[32:47], v[192:195], v[68:71], v[32:47]
	v_mfma_f32_32x32x16_bf16 v[32:47], v[214:217], v[72:75], v[32:47]
	v_mfma_f32_32x32x16_bf16 v[32:47], v[242:245], v[76:79], v[32:47]
	v_mfma_f32_32x32x16_bf16 v[16:31], v[88:91], v[64:67], v[16:31]
	v_mfma_f32_32x32x16_bf16 v[16:31], v[196:199], v[68:71], v[16:31]
	v_mfma_f32_32x32x16_bf16 v[16:31], v[230:233], v[72:75], v[16:31]
	v_mfma_f32_32x32x16_bf16 v[16:31], v[246:249], v[76:79], v[16:31]
	v_mfma_f32_32x32x16_bf16 v[0:15], v[92:95], v[64:67], v[0:15]
	v_mfma_f32_32x32x16_bf16 v[0:15], v[200:203], v[68:71], v[0:15]
	v_mfma_f32_32x32x16_bf16 v[0:15], v[234:237], v[72:75], v[0:15]
	v_mfma_f32_32x32x16_bf16 v[0:15], v[204:207], v[76:79], v[0:15]
	s_setprio 0
